# P0: w_sp source load issued before the x-loop and consumed after it (was a serialized load->wait->store after the x-loop), on v65
# speedup vs baseline: 1.0023x; 1.0023x over previous
; __device__ __forceinline__ unsigned f2bf(float f) { unsigned u = __builtin_bit_cast(unsigned, f); return (u + 0x7fffu + ((u >> 16) & 1u)) >> 16; }
; __device__ __forceinline__ unsigned pk2(float lo, float hi) { return pg8::cvt_pk_bf16(lo, hi); }
; __global__ void __launch_bounds__(NT, 2) fwd_mega(Args A) {
;     ...
;         for (int m = gw; m < T; m += NGW) {
;             const float* xrow = (m < 8192) ? A.xp + (size_t)m * D : A.xs + (size_t)(m - 8192) * D;
;             const f32x4* xr = (const f32x4*)xrow + lane; f32x4 v[8]; float s = 0.f;
; #pragma unroll
;             for (int j = 0; j < 8; ++j) { v[j] = __builtin_nontemporal_load(xr + 64 * j); s += (v[j][0] * v[j][0] + v[j][1] * v[j][1]) + (v[j][2] * v[j][2] + v[j][3] * v[j][3]); }
;             s = wave_sum(s);
;             if (lane == 0) r1[m] = 1.0f / sqrtf(s * (1.0f / D) + pg8::EPSN);
;             v2u* o8 = (v2u*)(XB + (size_t)m * D) + lane;
; #pragma unroll
;             for (int j = 0; j < 8; ++j) { v2u w; w.x = pk2(v[j][0], v[j][1]); w.y = pk2(v[j][2], v[j][3]); o8[64 * j] = w; }
;         }
;         const int gt = vcu * NT + tid, NGT = G * NT;
;         for (int i = gt; i < 8 * 128 * 128; i += NGT) ((bf16*)(ws + WS_WSP))[i] = (bf16)f2bf(A.w_sp[i]);
.Lcva_fin:
.Lcva_end:
.LBB0_59:
	v_lshl_add_u32 v240, s3, 9, v160
	v_ashrrev_i32_e32 v241, 31, v240
	v_lshl_add_u64 v[242:243], v[240:241], 2, s[10:11]
	global_load_dword v244, v[242:243], off
	s_cmpk_gt_i32 s58, 0x3fff
	v_mbcnt_lo_u32_b32 v161, -1, 0
	s_cbranch_scc1 .LBB0_64
	v_mbcnt_hi_u32_b32 v0, -1, v161
	v_and_b32_e32 v1, 64, v0
	v_add_u32_e32 v1, 64, v1
	v_xor_b32_e32 v2, 1, v0
	v_cmp_lt_i32_e32 vcc, v2, v1
	s_ashr_i32 s59, s58, 31
	s_lshl_b64 s[0:1], s[58:59], 12
	v_cndmask_b32_e32 v2, v0, v2, vcc
	v_lshlrev_b32_e32 v36, 2, v2
	v_xor_b32_e32 v2, 2, v0
	v_cmp_lt_i32_e32 vcc, v2, v1
	s_ashr_i32 s53, s52, 31
	v_lshl_or_b32 v34, v152, 3, s0
	v_cndmask_b32_e32 v2, v0, v2, vcc
	v_lshlrev_b32_e32 v37, 2, v2
	v_xor_b32_e32 v2, 4, v0
	v_cmp_lt_i32_e32 vcc, v2, v1
	v_mov_b32_e32 v35, s1
	s_lshl_b64 s[40:41], s[52:53], 12
	v_cndmask_b32_e32 v2, v0, v2, vcc
	v_lshlrev_b32_e32 v38, 2, v2
	v_xor_b32_e32 v2, 8, v0
	v_cmp_lt_i32_e32 vcc, v2, v1
	s_lshl_b64 s[0:1], s[58:59], 2
	s_add_u32 s0, s0, 0x30000
	v_cndmask_b32_e32 v2, v0, v2, vcc
	v_lshlrev_b32_e32 v39, 2, v2
	v_xor_b32_e32 v2, 16, v0
	v_cmp_lt_i32_e32 vcc, v2, v1
	v_mov_b32_e32 v33, 0
	v_cmp_eq_u32_e64 s[4:5], 0, v152
	v_cndmask_b32_e32 v2, v0, v2, vcc
	v_lshlrev_b32_e32 v40, 2, v2
	v_xor_b32_e32 v2, 32, v0
	v_cmp_lt_i32_e32 vcc, v2, v1
	s_addc_u32 s1, s1, 0
	s_lshl_b64 s[42:43], s[52:53], 2
	v_cndmask_b32_e32 v0, v0, v2, vcc
	v_lshlrev_b32_e32 v41, 2, v0
	v_lshlrev_b32_e32 v32, 4, v152
	s_movk_i32 s62, 0x1000
	v_mov_b32_e32 v42, 0x358637bd
	s_mov_b32 s63, 0xf800000
	v_mov_b32_e32 v43, 0x260
	s_branch .LBB0_62

; __device__ __forceinline__ unsigned f2bf(float f) { unsigned u = __builtin_bit_cast(unsigned, f); return (u + 0x7fffu + ((u >> 16) & 1u)) >> 16; }
; __global__ void __launch_bounds__(NT, 2) fwd_mega(Args A) {
;     ...
;         for (int i = gt; i < 8 * 128 * 128; i += NGT) ((bf16*)(ws + WS_WSP))[i] = (bf16)f2bf(A.w_sp[i]);
.LBB0_71:
	v_mov_b32_e32 v3, v244
	v_add_u32_e32 v2, s6, v2
	v_cmp_lt_i32_e32 vcc, s1, v2
	v_lshl_add_u64 v[4:5], v[4:5], 0, s[4:5]
	s_or_b64 s[38:39], vcc, s[38:39]
	s_nop 0
	v_bfe_u32 v9, v3, 16, 1
	v_add3_u32 v3, v3, v9, s0
	global_store_short_d16_hi v[6:7], v3, off
	v_lshl_add_u64 v[6:7], v[6:7], 0, s[10:11]
	s_andn2_b64 exec, exec, s[38:39]
	s_cbranch_execnz .LBB0_71
